# in-proj K-loop: one s_nop re-phases the fourth MFMA segment (32 MFMAs) from 4 mod 8 to 0 mod 8 bytes; a second keeps all later code at its phase
# speedup vs baseline: 1.0091x; 1.0091x over previous
.LBB0_129:
	ds_read_b128 v[132:135], v155
	ds_read_b128 v[136:139], v155 offset:1024
	ds_read_b128 v[140:143], v155 offset:2048
	ds_read_b128 v[160:163], v155 offset:3072
	ds_read_b128 v[164:167], v156
	ds_read_b128 v[168:171], v156 offset:1024
	ds_read_b128 v[172:175], v156 offset:2048
	ds_read_b128 v[176:179], v156 offset:3072
	s_cmp_eq_u32 s82, 28
	s_cselect_b32 s36, s27, s78
	s_cselect_b32 s37, s21, s79
	s_cselect_b32 s34, s77, s80
	s_cselect_b32 s35, s19, s81
	s_add_u32 s30, s36, 0x8000
	s_addc_u32 s31, s37, 0
	ds_read_b128 v[180:183], v157
	ds_read_b128 v[184:187], v157 offset:1024
	ds_read_b128 v[188:191], v157 offset:2048
	ds_read_b128 v[192:195], v157 offset:3072
	ds_read_b128 v[196:199], v157 offset:4096
	ds_read_b128 v[200:203], v157 offset:5120
	ds_read_b128 v[204:207], v157 offset:6144
	ds_read_b128 v[208:211], v157 offset:7168
	s_add_u32 s84, s78, 0xffffc000
	s_addc_u32 s85, s79, -1
	s_mov_b32 m0, s74
	s_nop 0
	global_load_lds_dwordx4 v151, s[84:85]
	s_nop 0
	s_mov_b32 m0, s75
	s_nop 0
	global_load_lds_dwordx4 v153, s[84:85]
	s_waitcnt vmcnt(8)
	s_waitcnt lgkmcnt(0)
	s_setprio 1
	s_barrier
	v_mfma_i32_16x16x64_i8 v[124:127], v[132:135], v[180:183], v[124:127]
	v_mfma_i32_16x16x64_i8 v[124:127], v[136:139], v[184:187], v[124:127]
	v_mfma_i32_16x16x64_i8 v[120:123], v[140:143], v[180:183], v[120:123]
	v_mfma_i32_16x16x64_i8 v[120:123], v[160:163], v[184:187], v[120:123]
	v_mfma_i32_16x16x64_i8 v[112:115], v[140:143], v[188:191], v[112:115]
	v_mfma_i32_16x16x64_i8 v[112:115], v[160:163], v[192:195], v[112:115]
	v_mfma_i32_16x16x64_i8 v[116:119], v[132:135], v[188:191], v[116:119]
	v_mfma_i32_16x16x64_i8 v[116:119], v[136:139], v[192:195], v[116:119]
	v_mfma_i32_16x16x64_i8 v[108:111], v[132:135], v[196:199], v[108:111]
	v_mfma_i32_16x16x64_i8 v[108:111], v[136:139], v[200:203], v[108:111]
	v_mfma_i32_16x16x64_i8 v[104:107], v[140:143], v[196:199], v[104:107]
	v_mfma_i32_16x16x64_i8 v[104:107], v[160:163], v[200:203], v[104:107]
	v_mfma_i32_16x16x64_i8 v[96:99], v[140:143], v[204:207], v[96:99]
	v_mfma_i32_16x16x64_i8 v[96:99], v[160:163], v[208:211], v[96:99]
	v_mfma_i32_16x16x64_i8 v[100:103], v[132:135], v[204:207], v[100:103]
	v_mfma_i32_16x16x64_i8 v[100:103], v[136:139], v[208:211], v[100:103]
	s_setprio 0
	s_setprio 1
	v_mfma_i32_16x16x64_i8 v[92:95], v[164:167], v[180:183], v[92:95]
	v_mfma_i32_16x16x64_i8 v[92:95], v[168:171], v[184:187], v[92:95]
	v_mfma_i32_16x16x64_i8 v[88:91], v[172:175], v[180:183], v[88:91]
	v_mfma_i32_16x16x64_i8 v[88:91], v[176:179], v[184:187], v[88:91]
	v_mfma_i32_16x16x64_i8 v[80:83], v[172:175], v[188:191], v[80:83]
	v_mfma_i32_16x16x64_i8 v[80:83], v[176:179], v[192:195], v[80:83]
	v_mfma_i32_16x16x64_i8 v[84:87], v[164:167], v[188:191], v[84:87]
	v_mfma_i32_16x16x64_i8 v[84:87], v[168:171], v[192:195], v[84:87]
	v_mfma_i32_16x16x64_i8 v[76:79], v[164:167], v[196:199], v[76:79]
	v_mfma_i32_16x16x64_i8 v[76:79], v[168:171], v[200:203], v[76:79]
	v_mfma_i32_16x16x64_i8 v[72:75], v[172:175], v[196:199], v[72:75]
	v_mfma_i32_16x16x64_i8 v[72:75], v[176:179], v[200:203], v[72:75]
	v_mfma_i32_16x16x64_i8 v[64:67], v[172:175], v[204:207], v[64:67]
	v_mfma_i32_16x16x64_i8 v[64:67], v[176:179], v[208:211], v[64:67]
	v_mfma_i32_16x16x64_i8 v[68:71], v[164:167], v[204:207], v[68:71]
	v_mfma_i32_16x16x64_i8 v[68:71], v[168:171], v[208:211], v[68:71]
	s_setprio 0
	s_barrier
	ds_read_b128 v[180:183], v157 offset:16384
	ds_read_b128 v[184:187], v157 offset:17408
	ds_read_b128 v[188:191], v157 offset:18432
	ds_read_b128 v[192:195], v157 offset:19456
	ds_read_b128 v[196:199], v157 offset:20480
	ds_read_b128 v[200:203], v157 offset:21504
	ds_read_b128 v[204:207], v157 offset:22528
	ds_read_b128 v[208:211], v157 offset:23552
	s_mov_b32 m0, s29
	s_nop 0
	global_load_lds_dwordx4 v152, s[34:35]
	s_add_u32 s84, s34, 0x4000
	s_mov_b32 m0, s62
	s_nop 0
	global_load_lds_dwordx4 v154, s[34:35]
	s_addc_u32 s85, s35, 0
	s_mov_b32 m0, s63
	s_nop 0
	global_load_lds_dwordx4 v152, s[84:85]
	s_nop 0
	s_mov_b32 m0, s64
	s_nop 0
	global_load_lds_dwordx4 v154, s[84:85]
	s_nop 0
	s_mov_b32 m0, s61
	s_nop 0
	global_load_lds_dwordx4 v151, s[36:37]
	s_nop 0
	s_mov_b32 m0, s65
	s_nop 0
	global_load_lds_dwordx4 v153, s[36:37]
	s_waitcnt vmcnt(8)
	s_waitcnt lgkmcnt(0)
	s_setprio 1
	s_barrier
	v_mfma_i32_16x16x64_i8 v[60:63], v[132:135], v[180:183], v[60:63]
	v_mfma_i32_16x16x64_i8 v[60:63], v[136:139], v[184:187], v[60:63]
	v_mfma_i32_16x16x64_i8 v[56:59], v[140:143], v[180:183], v[56:59]
	v_mfma_i32_16x16x64_i8 v[56:59], v[160:163], v[184:187], v[56:59]
	v_mfma_i32_16x16x64_i8 v[48:51], v[140:143], v[188:191], v[48:51]
	v_mfma_i32_16x16x64_i8 v[48:51], v[160:163], v[192:195], v[48:51]
	v_mfma_i32_16x16x64_i8 v[52:55], v[132:135], v[188:191], v[52:55]
	v_mfma_i32_16x16x64_i8 v[52:55], v[136:139], v[192:195], v[52:55]
	v_mfma_i32_16x16x64_i8 v[44:47], v[132:135], v[196:199], v[44:47]
	v_mfma_i32_16x16x64_i8 v[44:47], v[136:139], v[200:203], v[44:47]
	v_mfma_i32_16x16x64_i8 v[40:43], v[140:143], v[196:199], v[40:43]
	v_mfma_i32_16x16x64_i8 v[40:43], v[160:163], v[200:203], v[40:43]
	v_mfma_i32_16x16x64_i8 v[32:35], v[140:143], v[204:207], v[32:35]
	v_mfma_i32_16x16x64_i8 v[32:35], v[160:163], v[208:211], v[32:35]
	v_mfma_i32_16x16x64_i8 v[36:39], v[132:135], v[204:207], v[36:39]
	v_mfma_i32_16x16x64_i8 v[36:39], v[136:139], v[208:211], v[36:39]
	s_setprio 0
	s_setprio 1
	v_mfma_i32_16x16x64_i8 v[28:31], v[164:167], v[180:183], v[28:31]
	v_mfma_i32_16x16x64_i8 v[28:31], v[168:171], v[184:187], v[28:31]
	v_mfma_i32_16x16x64_i8 v[24:27], v[172:175], v[180:183], v[24:27]
	v_mfma_i32_16x16x64_i8 v[24:27], v[176:179], v[184:187], v[24:27]
	v_mfma_i32_16x16x64_i8 v[16:19], v[172:175], v[188:191], v[16:19]
	v_mfma_i32_16x16x64_i8 v[16:19], v[176:179], v[192:195], v[16:19]
	v_mfma_i32_16x16x64_i8 v[20:23], v[164:167], v[188:191], v[20:23]
	v_mfma_i32_16x16x64_i8 v[20:23], v[168:171], v[192:195], v[20:23]
	v_mfma_i32_16x16x64_i8 v[12:15], v[164:167], v[196:199], v[12:15]
	v_mfma_i32_16x16x64_i8 v[12:15], v[168:171], v[200:203], v[12:15]
	v_mfma_i32_16x16x64_i8 v[8:11], v[172:175], v[196:199], v[8:11]
	v_mfma_i32_16x16x64_i8 v[8:11], v[176:179], v[200:203], v[8:11]
	v_mfma_i32_16x16x64_i8 v[0:3], v[172:175], v[204:207], v[0:3]
	v_mfma_i32_16x16x64_i8 v[0:3], v[176:179], v[208:211], v[0:3]
	v_mfma_i32_16x16x64_i8 v[4:7], v[164:167], v[204:207], v[4:7]
	v_mfma_i32_16x16x64_i8 v[4:7], v[168:171], v[208:211], v[4:7]
	s_setprio 0
	s_barrier
	ds_read_b128 v[132:135], v158
	ds_read_b128 v[136:139], v158 offset:1024
	ds_read_b128 v[140:143], v158 offset:2048
	ds_read_b128 v[160:163], v158 offset:3072
	ds_read_b128 v[164:167], v159
	ds_read_b128 v[168:171], v159 offset:1024
	ds_read_b128 v[172:175], v159 offset:2048
	ds_read_b128 v[176:179], v159 offset:3072
	ds_read_b128 v[180:183], v157 offset:32768
	ds_read_b128 v[184:187], v157 offset:33792
	ds_read_b128 v[188:191], v157 offset:34816
	ds_read_b128 v[192:195], v157 offset:35840
	ds_read_b128 v[196:199], v157 offset:36864
	ds_read_b128 v[200:203], v157 offset:37888
	ds_read_b128 v[204:207], v157 offset:38912
	ds_read_b128 v[208:211], v157 offset:39936
	s_add_u32 s36, s36, 0x4000
	s_addc_u32 s37, s37, 0
	s_mov_b32 m0, s66
	s_nop 0
	global_load_lds_dwordx4 v151, s[36:37]
	s_nop 0
	s_mov_b32 m0, s67
	s_nop 0
	global_load_lds_dwordx4 v153, s[36:37]
	s_waitcnt vmcnt(8)
	s_waitcnt lgkmcnt(0)
	s_setprio 1
	s_barrier
	v_mfma_i32_16x16x64_i8 v[124:127], v[132:135], v[180:183], v[124:127]
	v_mfma_i32_16x16x64_i8 v[124:127], v[136:139], v[184:187], v[124:127]
	v_mfma_i32_16x16x64_i8 v[120:123], v[140:143], v[180:183], v[120:123]
	v_mfma_i32_16x16x64_i8 v[120:123], v[160:163], v[184:187], v[120:123]
	v_mfma_i32_16x16x64_i8 v[112:115], v[140:143], v[188:191], v[112:115]
	v_mfma_i32_16x16x64_i8 v[112:115], v[160:163], v[192:195], v[112:115]
	v_mfma_i32_16x16x64_i8 v[116:119], v[132:135], v[188:191], v[116:119]
	v_mfma_i32_16x16x64_i8 v[116:119], v[136:139], v[192:195], v[116:119]
	v_mfma_i32_16x16x64_i8 v[108:111], v[132:135], v[196:199], v[108:111]
	v_mfma_i32_16x16x64_i8 v[108:111], v[136:139], v[200:203], v[108:111]
	v_mfma_i32_16x16x64_i8 v[104:107], v[140:143], v[196:199], v[104:107]
	v_mfma_i32_16x16x64_i8 v[104:107], v[160:163], v[200:203], v[104:107]
	v_mfma_i32_16x16x64_i8 v[96:99], v[140:143], v[204:207], v[96:99]
	v_mfma_i32_16x16x64_i8 v[96:99], v[160:163], v[208:211], v[96:99]
	v_mfma_i32_16x16x64_i8 v[100:103], v[132:135], v[204:207], v[100:103]
	v_mfma_i32_16x16x64_i8 v[100:103], v[136:139], v[208:211], v[100:103]
	s_setprio 0
	s_setprio 1
	v_mfma_i32_16x16x64_i8 v[92:95], v[164:167], v[180:183], v[92:95]
	v_mfma_i32_16x16x64_i8 v[92:95], v[168:171], v[184:187], v[92:95]
	v_mfma_i32_16x16x64_i8 v[88:91], v[172:175], v[180:183], v[88:91]
	v_mfma_i32_16x16x64_i8 v[88:91], v[176:179], v[184:187], v[88:91]
	v_mfma_i32_16x16x64_i8 v[80:83], v[172:175], v[188:191], v[80:83]
	v_mfma_i32_16x16x64_i8 v[80:83], v[176:179], v[192:195], v[80:83]
	v_mfma_i32_16x16x64_i8 v[84:87], v[164:167], v[188:191], v[84:87]
	v_mfma_i32_16x16x64_i8 v[84:87], v[168:171], v[192:195], v[84:87]
	v_mfma_i32_16x16x64_i8 v[76:79], v[164:167], v[196:199], v[76:79]
	v_mfma_i32_16x16x64_i8 v[76:79], v[168:171], v[200:203], v[76:79]
	v_mfma_i32_16x16x64_i8 v[72:75], v[172:175], v[196:199], v[72:75]
	v_mfma_i32_16x16x64_i8 v[72:75], v[176:179], v[200:203], v[72:75]
	v_mfma_i32_16x16x64_i8 v[64:67], v[172:175], v[204:207], v[64:67]
	v_mfma_i32_16x16x64_i8 v[64:67], v[176:179], v[208:211], v[64:67]
	v_mfma_i32_16x16x64_i8 v[68:71], v[164:167], v[204:207], v[68:71]
	v_mfma_i32_16x16x64_i8 v[68:71], v[168:171], v[208:211], v[68:71]
	s_setprio 0
	s_barrier
	ds_read_b128 v[180:183], v157 offset:49152
	ds_read_b128 v[184:187], v157 offset:50176
	ds_read_b128 v[188:191], v157 offset:51200
	ds_read_b128 v[192:195], v157 offset:52224
	ds_read_b128 v[196:199], v157 offset:53248
	ds_read_b128 v[200:203], v157 offset:54272
	ds_read_b128 v[204:207], v157 offset:55296
	ds_read_b128 v[208:211], v157 offset:56320
	s_add_u32 s36, s34, 0x8000
	s_addc_u32 s37, s35, 0
	s_mov_b32 m0, s68
	s_nop 0
	global_load_lds_dwordx4 v152, s[36:37]
	s_add_u32 s34, s34, 0xc000
	s_mov_b32 m0, s69
	s_nop 0
	global_load_lds_dwordx4 v154, s[36:37]
	s_addc_u32 s35, s35, 0
	s_mov_b32 m0, s72
	s_nop 0
	global_load_lds_dwordx4 v152, s[34:35]
	s_nop 0
	s_mov_b32 m0, s73
	s_nop 0
	global_load_lds_dwordx4 v154, s[34:35]
	s_nop 0
	s_mov_b32 m0, s70
	s_nop 0
	global_load_lds_dwordx4 v151, s[30:31]
	s_nop 0
	s_mov_b32 m0, s71
	s_nop 0
	global_load_lds_dwordx4 v153, s[30:31]
	s_nop 0
	s_waitcnt vmcnt(8)
	s_waitcnt lgkmcnt(0)
	s_setprio 1
	s_barrier
	v_mfma_i32_16x16x64_i8 v[60:63], v[132:135], v[180:183], v[60:63]
	v_mfma_i32_16x16x64_i8 v[60:63], v[136:139], v[184:187], v[60:63]
	v_mfma_i32_16x16x64_i8 v[56:59], v[140:143], v[180:183], v[56:59]
	v_mfma_i32_16x16x64_i8 v[56:59], v[160:163], v[184:187], v[56:59]
	v_mfma_i32_16x16x64_i8 v[48:51], v[140:143], v[188:191], v[48:51]
	v_mfma_i32_16x16x64_i8 v[48:51], v[160:163], v[192:195], v[48:51]
	v_mfma_i32_16x16x64_i8 v[52:55], v[132:135], v[188:191], v[52:55]
	v_mfma_i32_16x16x64_i8 v[52:55], v[136:139], v[192:195], v[52:55]
	v_mfma_i32_16x16x64_i8 v[44:47], v[132:135], v[196:199], v[44:47]
	v_mfma_i32_16x16x64_i8 v[44:47], v[136:139], v[200:203], v[44:47]
	v_mfma_i32_16x16x64_i8 v[40:43], v[140:143], v[196:199], v[40:43]
	v_mfma_i32_16x16x64_i8 v[40:43], v[160:163], v[200:203], v[40:43]
	v_mfma_i32_16x16x64_i8 v[32:35], v[140:143], v[204:207], v[32:35]
	v_mfma_i32_16x16x64_i8 v[32:35], v[160:163], v[208:211], v[32:35]
	v_mfma_i32_16x16x64_i8 v[36:39], v[132:135], v[204:207], v[36:39]
	v_mfma_i32_16x16x64_i8 v[36:39], v[136:139], v[208:211], v[36:39]
	s_setprio 0
	s_setprio 1
	v_mfma_i32_16x16x64_i8 v[28:31], v[164:167], v[180:183], v[28:31]
	v_mfma_i32_16x16x64_i8 v[28:31], v[168:171], v[184:187], v[28:31]
	v_mfma_i32_16x16x64_i8 v[24:27], v[172:175], v[180:183], v[24:27]
	v_mfma_i32_16x16x64_i8 v[24:27], v[176:179], v[184:187], v[24:27]
	v_mfma_i32_16x16x64_i8 v[16:19], v[172:175], v[188:191], v[16:19]
	v_mfma_i32_16x16x64_i8 v[16:19], v[176:179], v[192:195], v[16:19]
	v_mfma_i32_16x16x64_i8 v[20:23], v[164:167], v[188:191], v[20:23]
	v_mfma_i32_16x16x64_i8 v[20:23], v[168:171], v[192:195], v[20:23]
	v_mfma_i32_16x16x64_i8 v[12:15], v[164:167], v[196:199], v[12:15]
	v_mfma_i32_16x16x64_i8 v[12:15], v[168:171], v[200:203], v[12:15]
	v_mfma_i32_16x16x64_i8 v[8:11], v[172:175], v[196:199], v[8:11]
	v_mfma_i32_16x16x64_i8 v[8:11], v[176:179], v[200:203], v[8:11]
	v_mfma_i32_16x16x64_i8 v[0:3], v[172:175], v[204:207], v[0:3]
	v_mfma_i32_16x16x64_i8 v[0:3], v[176:179], v[208:211], v[0:3]
	v_mfma_i32_16x16x64_i8 v[4:7], v[164:167], v[204:207], v[4:7]
	v_mfma_i32_16x16x64_i8 v[4:7], v[168:171], v[208:211], v[4:7]
	s_setprio 0
	s_barrier
	s_nop 0
	s_add_i32 s82, s82, 2
	s_add_u32 s78, s78, 0x10000
	s_addc_u32 s79, s79, 0
	s_add_u32 s80, s80, 0x10000
	s_addc_u32 s81, s81, 0
	s_cmp_gt_u32 s82, 29
	s_cbranch_scc0 .LBB0_129
	s_and_b64 vcc, exec, s[14:15]
	s_cbranch_vccz .LBB0_132
	s_barrier
